# MLA loop: K reads hoisted to loop top, acc-init trimmed to 16 movs, first two blk1 K fragments prefetched into v248-255 during PV0
# baseline (speedup 1.0000x reference)
; #define LAS __attribute__((address_space(3)))
; DI float xmax32(float v) { return fmaxf(v, __shfl_xor(v, 32)); }
; DI float fast_exp2(float x) { return __builtin_amdgcn_exp2f(x); }
; template <int NDB>
; DI void softmax_only(f32x16& sacc, float& m, float& l, f32x16 (&oacc)[NDB], bf16x8 (&pf)[2]) {
;     float mx = sacc[0];
; #pragma unroll
;     for (int i = 1; i < 16; ++i) mx = fmaxf(mx, sacc[i]);
;     mx = xmax32(mx);
;     if (__any(mx > 8.0f)) {
;         const float d = fmaxf(mx, 0.f), alpha = fast_exp2(-d);
;         l *= alpha; m += d;
; #pragma unroll
;         for (int i = 0; i < 16; ++i) sacc[i] -= d;
; #pragma unroll
;         for (int db = 0; db < NDB; ++db)
; #pragma unroll
;             for (int i = 0; i < 16; ++i) oacc[db][i] *= alpha;
;     }
; DI void mla_attn_phase(const Params& p, LAS unsigned char* lds) {
;     ...
;         for (int t = 0; t < NT; ++t) {
;             if (t + 1 < NT) MLA_LOAD((t + 1) * 64);
;             LAS unsigned char* kb = lds + (t & 1) * BUF;
; #pragma unroll
;             for (int blk = 0; blk < 2; ++blk) {
;                 bf16x8 kf[12];
;                 LAS const unsigned char* kp = kb + (blk * 32 + r) * KSTR + h * 16;
; #pragma unroll
;                 for (int ks = 0; ks < 4; ++ks) kf[ks] = *(LAS const bf16x8*)(kp + ks * 32);
;                 f32x16 sacc;
; #pragma unroll
;                 for (int i = 0; i < 16; ++i) sacc[i] = -m;
; #pragma unroll
;                 for (int kg = 0; kg < 3; ++kg) {
;                     if (kg < 2) {
; #pragma unroll
;                         for (int ks = 0; ks < 4; ++ks) kf[4 * (kg + 1) + ks] = *(LAS const bf16x8*)(kp + (4 * (kg + 1) + ks) * 32);
;                     }
; #pragma unroll
;                     for (int ks = 0; ks < 4; ++ks) sacc = __builtin_amdgcn_mfma_f32_32x32x16_bf16(kf[4 * kg + ks], qf[4 * kg + ks], sacc, 0, 0, 0);
;                 }
;                 bf16x8 vf[2][4], pf[2];
;                 load_vfrags<4, VSTR>(vf, kb + KBUF + r * VSTR + blk * 64 + h * 16);
;                 softmax_only<4>(sacc, m, l, oacc, pf);
.LBB1_1685:
	s_bitcmp1_b32 s2, 0
	s_cselect_b32 s3, 0xac00, 0
	v_add_u32_e32 v64, s3, v206
	v_add_u32_e32 v244, v64, v213
	ds_read_b128 v[164:167], v244
	ds_read_b128 v[168:171], v244 offset:32
	ds_read_b128 v[172:175], v244 offset:64
	ds_read_b128 v[176:179], v244 offset:96
	ds_read_b128 v[180:183], v244 offset:128
	ds_read_b128 v[184:187], v244 offset:160
	ds_read_b128 v[188:191], v244 offset:192
	ds_read_b128 v[192:195], v244 offset:224
	v_lshl_add_u64 v[64:65], s[40:41], 0, v[226:227]
	v_add_co_u32_e32 v66, vcc, 0x40516000, v64
	s_nop 1
	v_addc_co_u32_e32 v67, vcc, 0, v65, vcc
	global_load_dwordx4 v[156:159], v[66:67], off
	v_add_co_u32_e32 v66, vcc, 0x40518000, v64
	s_nop 1
	v_addc_co_u32_e32 v67, vcc, 0, v65, vcc
	v_add_co_u32_e32 v64, vcc, 0x4051a000, v64
	global_load_dwordx4 v[152:155], v[66:67], off
	s_nop 0
	v_addc_co_u32_e32 v65, vcc, 0, v65, vcc
	global_load_dwordx4 v[160:163], v[64:65], off
	v_lshl_add_u64 v[64:65], s[40:41], 0, v[224:225]
	global_load_dwordx4 v[148:151], v[64:65], off
	v_lshl_add_u64 v[64:65], s[40:41], 0, v[222:223]
	global_load_dwordx4 v[144:147], v[64:65], off
	v_add_u32_e32 v65, s3, v207
	v_add_u32_e32 v243, v65, v206
	v_xor_b32_e32 v64, 0x80000000, v221
	v_mov_b32_e32 v80, v64
	v_mov_b32_e32 v81, v64
	v_mov_b32_e32 v82, v64
	v_mov_b32_e32 v83, v64
	v_mov_b32_e32 v84, v64
	v_mov_b32_e32 v85, v64
	v_mov_b32_e32 v86, v64
	v_mov_b32_e32 v87, v64
	v_mov_b32_e32 v88, v64
	v_mov_b32_e32 v89, v64
	v_mov_b32_e32 v90, v64
	v_mov_b32_e32 v91, v64
	v_mov_b32_e32 v92, v64
	v_mov_b32_e32 v93, v64
	v_mov_b32_e32 v94, v64
	v_mov_b32_e32 v95, v64
	s_nop 1
	s_waitcnt lgkmcnt(7)
	v_mfma_f32_32x32x16_bf16 v[80:95], v[164:167], v[140:143], v[80:95]
	ds_read_b128 v[66:69], v244 offset:256
	ds_read_b128 v[70:73], v244 offset:288
	ds_read_b128 v[74:77], v244 offset:320
	ds_read_b128 v[164:167], v244 offset:352
	s_waitcnt lgkmcnt(10)
	v_mfma_f32_32x32x16_bf16 v[80:95], v[168:171], v[136:139], v[80:95]
	s_waitcnt lgkmcnt(9)
	v_mfma_f32_32x32x16_bf16 v[80:95], v[172:175], v[132:135], v[80:95]
	s_waitcnt lgkmcnt(8)
	v_mfma_f32_32x32x16_bf16 v[80:95], v[176:179], v[128:131], v[80:95]
	s_waitcnt lgkmcnt(7)
	v_mfma_f32_32x32x16_bf16 v[80:95], v[180:183], v[124:127], v[80:95]
	s_waitcnt lgkmcnt(6)
	v_mfma_f32_32x32x16_bf16 v[80:95], v[184:187], v[120:123], v[80:95]
	s_waitcnt lgkmcnt(5)
	v_mfma_f32_32x32x16_bf16 v[80:95], v[188:191], v[116:119], v[80:95]
	s_waitcnt lgkmcnt(4)
	v_mfma_f32_32x32x16_bf16 v[80:95], v[192:195], v[112:115], v[80:95]
	s_waitcnt lgkmcnt(3)
	v_mfma_f32_32x32x16_bf16 v[80:95], v[66:69], v[108:111], v[80:95]
	s_waitcnt lgkmcnt(2)
	v_mfma_f32_32x32x16_bf16 v[80:95], v[70:73], v[104:107], v[80:95]
	s_waitcnt lgkmcnt(1)
	v_mfma_f32_32x32x16_bf16 v[80:95], v[74:77], v[100:103], v[80:95]
	s_waitcnt lgkmcnt(0)
	v_mfma_f32_32x32x16_bf16 v[80:95], v[164:167], v[96:99], v[80:95]
	ds_read_b128 v[192:195], v243 offset:25600
	ds_read_b128 v[164:167], v243 offset:25632
	ds_read_b128 v[188:191], v243 offset:30208
	ds_read_b128 v[184:187], v243 offset:34816
	ds_read_b128 v[168:171], v243 offset:39424
	ds_read_b128 v[172:175], v243 offset:30240
	ds_read_b128 v[176:179], v243 offset:34848
	ds_read_b128 v[180:183], v243 offset:39456
	s_nop 3
	v_max_f32_e32 v65, v81, v81
	v_max_f32_e32 v66, v80, v80
	v_max_f32_e32 v65, v66, v65
	v_max3_f32 v65, v65, v82, v83
	v_max3_f32 v65, v65, v84, v85
	v_max3_f32 v65, v65, v86, v87
	v_max3_f32 v65, v65, v88, v89
	v_max3_f32 v65, v65, v90, v91
	v_max3_f32 v65, v65, v92, v93
	v_max3_f32 v65, v65, v94, v95
	v_mov_b32_e32 v66, v65
	s_nop 1
	v_permlane32_swap_b32_e32 v66, v65
	v_max_f32_e32 v65, v65, v66
	v_cmp_lt_f32_e32 vcc, s10, v65
	s_cbranch_vccz .LBB1_1687
	v_max_f32_e32 v64, v65, v65
	v_max_f32_e32 v64, 0, v64
	v_exp_f32_e64 v66, -v64
	v_add_f32_e32 v221, v221, v64
	v_pk_add_f32 v[80:81], v[80:81], v[64:65] op_sel_hi:[1,0] neg_lo:[0,1] neg_hi:[0,1]
	v_pk_add_f32 v[82:83], v[82:83], v[64:65] op_sel_hi:[1,0] neg_lo:[0,1] neg_hi:[0,1]
	v_mul_f32_e32 v242, v242, v66
	v_pk_add_f32 v[84:85], v[84:85], v[64:65] op_sel_hi:[1,0] neg_lo:[0,1] neg_hi:[0,1]
	v_pk_add_f32 v[86:87], v[86:87], v[64:65] op_sel_hi:[1,0] neg_lo:[0,1] neg_hi:[0,1]
	v_pk_add_f32 v[88:89], v[88:89], v[64:65] op_sel_hi:[1,0] neg_lo:[0,1] neg_hi:[0,1]
	v_pk_add_f32 v[90:91], v[90:91], v[64:65] op_sel_hi:[1,0] neg_lo:[0,1] neg_hi:[0,1]
	v_pk_add_f32 v[92:93], v[92:93], v[64:65] op_sel_hi:[1,0] neg_lo:[0,1] neg_hi:[0,1]
	v_pk_add_f32 v[94:95], v[94:95], v[64:65] op_sel_hi:[1,0] neg_lo:[0,1] neg_hi:[0,1]
	v_pk_mul_f32 v[62:63], v[62:63], v[66:67] op_sel_hi:[1,0]
	v_pk_mul_f32 v[60:61], v[60:61], v[66:67] op_sel_hi:[1,0]
	v_pk_mul_f32 v[58:59], v[58:59], v[66:67] op_sel_hi:[1,0]
	v_pk_mul_f32 v[56:57], v[56:57], v[66:67] op_sel_hi:[1,0]
	v_pk_mul_f32 v[54:55], v[54:55], v[66:67] op_sel_hi:[1,0]
	v_pk_mul_f32 v[52:53], v[52:53], v[66:67] op_sel_hi:[1,0]
	v_pk_mul_f32 v[50:51], v[50:51], v[66:67] op_sel_hi:[1,0]
	v_pk_mul_f32 v[48:49], v[48:49], v[66:67] op_sel_hi:[1,0]
	v_pk_mul_f32 v[46:47], v[46:47], v[66:67] op_sel_hi:[1,0]
	v_pk_mul_f32 v[44:45], v[44:45], v[66:67] op_sel_hi:[1,0]
	v_pk_mul_f32 v[42:43], v[42:43], v[66:67] op_sel_hi:[1,0]
	v_pk_mul_f32 v[40:41], v[40:41], v[66:67] op_sel_hi:[1,0]
	v_pk_mul_f32 v[38:39], v[38:39], v[66:67] op_sel_hi:[1,0]
	v_pk_mul_f32 v[36:37], v[36:37], v[66:67] op_sel_hi:[1,0]
	v_pk_mul_f32 v[34:35], v[34:35], v[66:67] op_sel_hi:[1,0]
	v_pk_mul_f32 v[32:33], v[32:33], v[66:67] op_sel_hi:[1,0]
	v_pk_mul_f32 v[30:31], v[30:31], v[66:67] op_sel_hi:[1,0]
	v_pk_mul_f32 v[28:29], v[28:29], v[66:67] op_sel_hi:[1,0]
	v_pk_mul_f32 v[26:27], v[26:27], v[66:67] op_sel_hi:[1,0]
	v_pk_mul_f32 v[24:25], v[24:25], v[66:67] op_sel_hi:[1,0]
	v_pk_mul_f32 v[22:23], v[22:23], v[66:67] op_sel_hi:[1,0]
	v_pk_mul_f32 v[20:21], v[20:21], v[66:67] op_sel_hi:[1,0]
	v_pk_mul_f32 v[18:19], v[18:19], v[66:67] op_sel_hi:[1,0]
	v_pk_mul_f32 v[16:17], v[16:17], v[66:67] op_sel_hi:[1,0]
	v_pk_mul_f32 v[14:15], v[14:15], v[66:67] op_sel_hi:[1,0]
	v_pk_mul_f32 v[12:13], v[12:13], v[66:67] op_sel_hi:[1,0]
	v_pk_mul_f32 v[10:11], v[10:11], v[66:67] op_sel_hi:[1,0]
	v_pk_mul_f32 v[8:9], v[8:9], v[66:67] op_sel_hi:[1,0]
	v_pk_mul_f32 v[6:7], v[6:7], v[66:67] op_sel_hi:[1,0]
	v_pk_mul_f32 v[4:5], v[4:5], v[66:67] op_sel_hi:[1,0]
	v_pk_mul_f32 v[2:3], v[2:3], v[66:67] op_sel_hi:[1,0]
	v_pk_mul_f32 v[0:1], v[0:1], v[66:67] op_sel_hi:[1,0]
	v_xor_b32_e32 v64, 0x80000000, v221
; #define LAS __attribute__((address_space(3)))
; DI unsigned pack2(float a, float b) { f32x2 v = {a, b}; hwbf16x2 r = __builtin_convertvector(v, hwbf16x2); return __builtin_bit_cast(unsigned, r); }
; DI float fast_exp2(float x) { return __builtin_amdgcn_exp2f(x); }
; template <int NDB>
; DI void softmax_only(f32x16& sacc, float& m, float& l, f32x16 (&oacc)[NDB], bf16x8 (&pf)[2]) {
;     ...
;     float pv[16], ls = 0.f;
; #pragma unroll
;     for (int i = 0; i < 16; ++i) { pv[i] = fast_exp2(sacc[i]); ls += pv[i]; }
;     l += ls;
; #pragma unroll
;     for (int s2 = 0; s2 < 2; ++s2) {
;         u32x4 pw;
; #pragma unroll
;         for (int q = 0; q < 4; ++q) pw[q] = pack2(pv[8 * s2 + 2 * q], pv[8 * s2 + 2 * q + 1]);
;         pf[s2] = __builtin_bit_cast(bf16x8, pw);
;     }
; DI void mla_attn_phase(const Params& p, LAS unsigned char* lds) {
;     ...
;             for (int blk = 0; blk < 2; ++blk) {
;                 bf16x8 kf[12];
;                 LAS const unsigned char* kp = kb + (blk * 32 + r) * KSTR + h * 16;
; #pragma unroll
;                 for (int ks = 0; ks < 4; ++ks) kf[ks] = *(LAS const bf16x8*)(kp + ks * 32);
;                 f32x16 sacc;
; #pragma unroll
;                 for (int i = 0; i < 16; ++i) sacc[i] = -m;
; #pragma unroll
;                 for (int kg = 0; kg < 3; ++kg) {
;                     if (kg < 2) {
; #pragma unroll
;                         for (int ks = 0; ks < 4; ++ks) kf[4 * (kg + 1) + ks] = *(LAS const bf16x8*)(kp + (4 * (kg + 1) + ks) * 32);
;                     }
; #pragma unroll
;                     for (int ks = 0; ks < 4; ++ks) sacc = __builtin_amdgcn_mfma_f32_32x32x16_bf16(kf[4 * kg + ks], qf[4 * kg + ks], sacc, 0, 0, 0);
;                 }
;                 bf16x8 vf[2][4], pf[2];
;                 load_vfrags<4, VSTR>(vf, kb + KBUF + r * VSTR + blk * 64 + h * 16);
;                 softmax_only<4>(sacc, m, l, oacc, pf);
; #pragma unroll
;                 for (int s2 = 0; s2 < 2; ++s2)
; #pragma unroll
;                     for (int db = 0; db < 4; ++db) oacc[db] = __builtin_amdgcn_mfma_f32_32x32x16_bf16(vf[s2][db], pf[s2], oacc[db], 0, 0, 0);
.LBB1_1687:
	v_exp_f32_e32 v80, v80
	v_exp_f32_e32 v81, v81
	v_exp_f32_e32 v82, v82
	v_exp_f32_e32 v83, v83
	v_add_f32_e32 v245, 0, v80
	v_exp_f32_e32 v84, v84
	v_add_f32_e32 v245, v245, v81
	v_exp_f32_e32 v85, v85
	v_add_f32_e32 v245, v82, v245
	v_exp_f32_e32 v86, v86
	v_exp_f32_e32 v87, v87
	v_add_f32_e32 v245, v83, v245
	v_add_f32_e32 v245, v84, v245
	v_exp_f32_e32 v88, v88
	v_add_f32_e32 v245, v85, v245
	v_exp_f32_e32 v89, v89
	v_add_f32_e32 v245, v86, v245
	v_exp_f32_e32 v90, v90
	v_cvt_pk_bf16_f32 v80, v80, v81
	v_cvt_pk_bf16_f32 v81, v82, v83
	v_cvt_pk_bf16_f32 v82, v84, v85
	v_cvt_pk_bf16_f32 v83, v86, v87
	v_add_f32_e32 v245, v87, v245
	v_exp_f32_e32 v91, v91
	s_waitcnt lgkmcnt(0)
	v_mfma_f32_32x32x16_bf16 v[48:63], v[192:195], v[80:83], v[48:63]
	ds_read_b128 v[248:251], v244 offset:12800
	ds_read_b128 v[252:255], v244 offset:12832
	v_add_f32_e32 v245, v88, v245
	v_exp_f32_e32 v92, v92
	v_add_f32_e32 v245, v89, v245
	v_exp_f32_e32 v93, v93
	v_add_f32_e32 v245, v90, v245
	v_exp_f32_e32 v94, v94
	v_exp_f32_e32 v95, v95
	v_mfma_f32_32x32x16_bf16 v[32:47], v[188:191], v[80:83], v[32:47]
	v_add_f32_e32 v245, v91, v245
	v_add_f32_e32 v245, v92, v245
	v_add_f32_e32 v245, v93, v245
	v_mov_b32_e32 v65, v64
	v_mov_b32_e32 v66, v64
	v_mov_b32_e32 v67, v64
	v_mov_b32_e32 v68, v64
	v_mfma_f32_32x32x16_bf16 v[16:31], v[184:187], v[80:83], v[16:31]
	v_mov_b32_e32 v69, v64
	v_mov_b32_e32 v70, v64
	v_mov_b32_e32 v71, v64
	v_mov_b32_e32 v72, v64
	v_mov_b32_e32 v73, v64
	v_mov_b32_e32 v74, v64
	v_mov_b32_e32 v75, v64
	v_mfma_f32_32x32x16_bf16 v[0:15], v[168:171], v[80:83], v[0:15]
	v_mov_b32_e32 v76, v64
	v_mov_b32_e32 v77, v64
	v_mov_b32_e32 v78, v64
	v_mov_b32_e32 v79, v64
	v_add_f32_e32 v245, v94, v245
	v_cvt_pk_bf16_f32 v84, v88, v89
	v_cvt_pk_bf16_f32 v85, v90, v91
	v_cvt_pk_bf16_f32 v86, v92, v93
	v_cvt_pk_bf16_f32 v87, v94, v95
	v_add_f32_e32 v245, v95, v245
	s_nop 0
	v_mfma_f32_32x32x16_bf16 v[48:63], v[164:167], v[84:87], v[48:63]
	v_mfma_f32_32x32x16_bf16 v[32:47], v[172:175], v[84:87], v[32:47]
	v_mfma_f32_32x32x16_bf16 v[16:31], v[176:179], v[84:87], v[16:31]
	v_mfma_f32_32x32x16_bf16 v[0:15], v[180:183], v[84:87], v[0:15]
	ds_read_b128 v[88:91], v244 offset:12864
	ds_read_b128 v[92:95], v244 offset:12896
	ds_read_b128 v[164:167], v244 offset:12928
	ds_read_b128 v[168:171], v244 offset:12960
	ds_read_b128 v[172:175], v244 offset:12992
	ds_read_b128 v[176:179], v244 offset:13024
	v_add_f32_e32 v180, v242, v245
	s_waitcnt lgkmcnt(7)
	v_mfma_f32_32x32x16_bf16 v[64:79], v[248:251], v[140:143], v[64:79]
	s_waitcnt lgkmcnt(6)
	v_mfma_f32_32x32x16_bf16 v[64:79], v[252:255], v[136:139], v[64:79]
	s_waitcnt lgkmcnt(5)
	v_mfma_f32_32x32x16_bf16 v[64:79], v[88:91], v[132:135], v[64:79]
	s_waitcnt lgkmcnt(4)
	v_mfma_f32_32x32x16_bf16 v[64:79], v[92:95], v[128:131], v[64:79]
	ds_read_b128 v[80:83], v244 offset:13056
	ds_read_b128 v[84:87], v244 offset:13088
	ds_read_b128 v[88:91], v244 offset:13120
	ds_read_b128 v[92:95], v244 offset:13152
	s_waitcnt lgkmcnt(7)
	v_mfma_f32_32x32x16_bf16 v[64:79], v[164:167], v[124:127], v[64:79]
	s_waitcnt lgkmcnt(6)
	v_mfma_f32_32x32x16_bf16 v[64:79], v[168:171], v[120:123], v[64:79]
	s_waitcnt lgkmcnt(5)
	v_mfma_f32_32x32x16_bf16 v[64:79], v[172:175], v[116:119], v[64:79]
	s_waitcnt lgkmcnt(4)
	v_mfma_f32_32x32x16_bf16 v[64:79], v[176:179], v[112:115], v[64:79]
	s_waitcnt lgkmcnt(3)
	v_mfma_f32_32x32x16_bf16 v[64:79], v[80:83], v[108:111], v[64:79]
	s_waitcnt lgkmcnt(2)
	v_mfma_f32_32x32x16_bf16 v[64:79], v[84:87], v[104:107], v[64:79]
	s_waitcnt lgkmcnt(1)
	v_mfma_f32_32x32x16_bf16 v[64:79], v[88:91], v[100:103], v[64:79]
	s_waitcnt lgkmcnt(0)
	v_mfma_f32_32x32x16_bf16 v[64:79], v[92:95], v[96:99], v[64:79]
	ds_read_b128 v[176:179], v243 offset:25664
	ds_read_b128 v[92:95], v243 offset:25696
	ds_read_b128 v[172:175], v243 offset:30272
	ds_read_b128 v[168:171], v243 offset:34880
	ds_read_b128 v[164:167], v243 offset:39488
	ds_read_b128 v[80:83], v243 offset:30304
	ds_read_b128 v[84:87], v243 offset:34912
	ds_read_b128 v[88:91], v243 offset:39520
	s_nop 3
	v_max_f32_e32 v181, v65, v65
	v_max_f32_e32 v182, v64, v64
	v_max_f32_e32 v181, v182, v181
	v_max3_f32 v181, v181, v66, v67
	v_max3_f32 v181, v181, v68, v69
	v_max3_f32 v181, v181, v70, v71
	v_max3_f32 v181, v181, v72, v73
	v_max3_f32 v181, v181, v74, v75
	v_max3_f32 v181, v181, v76, v77
	v_max3_f32 v181, v181, v78, v79
	v_mov_b32_e32 v182, v181
	s_nop 1
	v_permlane32_swap_b32_e32 v182, v181
	v_max_f32_e32 v181, v181, v182
	v_cmp_lt_f32_e32 vcc, s10, v181
	s_cbranch_vccz .LBB1_1684
; DI float fast_exp2(float x) { return __builtin_amdgcn_exp2f(x); }
; template <int NDB>
; DI void softmax_only(f32x16& sacc, float& m, float& l, f32x16 (&oacc)[NDB], bf16x8 (&pf)[2]) {
;     ...
;     if (__any(mx > 8.0f)) {
;         const float d = fmaxf(mx, 0.f), alpha = fast_exp2(-d);
;         l *= alpha; m += d;
; #pragma unroll
;         for (int i = 0; i < 16; ++i) sacc[i] -= d;
; #pragma unroll
;         for (int db = 0; db < NDB; ++db)
; #pragma unroll
;             for (int i = 0; i < 16; ++i) oacc[db][i] *= alpha;
;     }
	v_max_f32_e32 v181, v181, v181
	v_max_f32_e32 v182, 0, v181
	v_exp_f32_e64 v184, -v182
	v_add_f32_e32 v221, v221, v182
	v_pk_add_f32 v[64:65], v[64:65], v[182:183] op_sel_hi:[1,0] neg_lo:[0,1] neg_hi:[0,1]
	v_pk_add_f32 v[66:67], v[66:67], v[182:183] op_sel_hi:[1,0] neg_lo:[0,1] neg_hi:[0,1]
	v_mul_f32_e32 v180, v180, v184
	v_pk_add_f32 v[68:69], v[68:69], v[182:183] op_sel_hi:[1,0] neg_lo:[0,1] neg_hi:[0,1]
	v_pk_add_f32 v[70:71], v[70:71], v[182:183] op_sel_hi:[1,0] neg_lo:[0,1] neg_hi:[0,1]
	v_pk_add_f32 v[72:73], v[72:73], v[182:183] op_sel_hi:[1,0] neg_lo:[0,1] neg_hi:[0,1]
	v_pk_add_f32 v[74:75], v[74:75], v[182:183] op_sel_hi:[1,0] neg_lo:[0,1] neg_hi:[0,1]
	v_pk_add_f32 v[76:77], v[76:77], v[182:183] op_sel_hi:[1,0] neg_lo:[0,1] neg_hi:[0,1]
	v_pk_add_f32 v[78:79], v[78:79], v[182:183] op_sel_hi:[1,0] neg_lo:[0,1] neg_hi:[0,1]
	v_pk_mul_f32 v[62:63], v[62:63], v[184:185] op_sel_hi:[1,0]
	v_pk_mul_f32 v[60:61], v[60:61], v[184:185] op_sel_hi:[1,0]
	v_pk_mul_f32 v[58:59], v[58:59], v[184:185] op_sel_hi:[1,0]
	v_pk_mul_f32 v[56:57], v[56:57], v[184:185] op_sel_hi:[1,0]
	v_pk_mul_f32 v[54:55], v[54:55], v[184:185] op_sel_hi:[1,0]
	v_pk_mul_f32 v[52:53], v[52:53], v[184:185] op_sel_hi:[1,0]
	v_pk_mul_f32 v[50:51], v[50:51], v[184:185] op_sel_hi:[1,0]
	v_pk_mul_f32 v[48:49], v[48:49], v[184:185] op_sel_hi:[1,0]
	v_pk_mul_f32 v[46:47], v[46:47], v[184:185] op_sel_hi:[1,0]
	v_pk_mul_f32 v[44:45], v[44:45], v[184:185] op_sel_hi:[1,0]
	v_pk_mul_f32 v[42:43], v[42:43], v[184:185] op_sel_hi:[1,0]
	v_pk_mul_f32 v[40:41], v[40:41], v[184:185] op_sel_hi:[1,0]
	v_pk_mul_f32 v[38:39], v[38:39], v[184:185] op_sel_hi:[1,0]
	v_pk_mul_f32 v[36:37], v[36:37], v[184:185] op_sel_hi:[1,0]
	v_pk_mul_f32 v[34:35], v[34:35], v[184:185] op_sel_hi:[1,0]
	v_pk_mul_f32 v[32:33], v[32:33], v[184:185] op_sel_hi:[1,0]
	v_pk_mul_f32 v[30:31], v[30:31], v[184:185] op_sel_hi:[1,0]
	v_pk_mul_f32 v[28:29], v[28:29], v[184:185] op_sel_hi:[1,0]
	v_pk_mul_f32 v[26:27], v[26:27], v[184:185] op_sel_hi:[1,0]
	v_pk_mul_f32 v[24:25], v[24:25], v[184:185] op_sel_hi:[1,0]
	v_pk_mul_f32 v[22:23], v[22:23], v[184:185] op_sel_hi:[1,0]
	v_pk_mul_f32 v[20:21], v[20:21], v[184:185] op_sel_hi:[1,0]
	v_pk_mul_f32 v[18:19], v[18:19], v[184:185] op_sel_hi:[1,0]
	v_pk_mul_f32 v[16:17], v[16:17], v[184:185] op_sel_hi:[1,0]
	v_pk_mul_f32 v[14:15], v[14:15], v[184:185] op_sel_hi:[1,0]
	v_pk_mul_f32 v[12:13], v[12:13], v[184:185] op_sel_hi:[1,0]
	v_pk_mul_f32 v[10:11], v[10:11], v[184:185] op_sel_hi:[1,0]
	v_pk_mul_f32 v[8:9], v[8:9], v[184:185] op_sel_hi:[1,0]
	v_pk_mul_f32 v[6:7], v[6:7], v[184:185] op_sel_hi:[1,0]
	v_pk_mul_f32 v[4:5], v[4:5], v[184:185] op_sel_hi:[1,0]
	v_pk_mul_f32 v[2:3], v[2:3], v[184:185] op_sel_hi:[1,0]
	v_pk_mul_f32 v[0:1], v[0:1], v[184:185] op_sel_hi:[1,0]
	s_branch .LBB1_1684
